# stats_rows: the 4 rows per wave batched (loads issued together, shared butterfly rounds), same arithmetic
# baseline (speedup 1.0000x reference)
.LBB0_486:
	global_load_dwordx2 v[4:5], v[2:3], off
	v_lshl_add_u64 v[16:17], v[2:3], 0, s[16:17]
	global_load_dwordx2 v[18:19], v[16:17], off
	v_lshl_add_u64 v[16:17], v[16:17], 0, s[16:17]
	global_load_dwordx2 v[20:21], v[16:17], off
	v_lshl_add_u64 v[16:17], v[16:17], 0, s[16:17]
	global_load_dwordx2 v[22:23], v[16:17], off
	s_waitcnt vmcnt(0) lgkmcnt(0)
	ds_bpermute_b32 v6, v8, v4
	ds_bpermute_b32 v7, v8, v5
	ds_bpermute_b32 v24, v8, v18
	ds_bpermute_b32 v25, v8, v19
	ds_bpermute_b32 v26, v8, v20
	ds_bpermute_b32 v27, v8, v21
	ds_bpermute_b32 v28, v8, v22
	ds_bpermute_b32 v29, v8, v23
	s_waitcnt lgkmcnt(0)
	v_pk_add_f32 v[4:5], v[4:5], v[6:7]
	v_pk_add_f32 v[18:19], v[18:19], v[24:25]
	v_pk_add_f32 v[20:21], v[20:21], v[26:27]
	v_pk_add_f32 v[22:23], v[22:23], v[28:29]
	ds_bpermute_b32 v6, v9, v4
	ds_bpermute_b32 v7, v9, v5
	ds_bpermute_b32 v24, v9, v18
	ds_bpermute_b32 v25, v9, v19
	ds_bpermute_b32 v26, v9, v20
	ds_bpermute_b32 v27, v9, v21
	ds_bpermute_b32 v28, v9, v22
	ds_bpermute_b32 v29, v9, v23
	s_waitcnt lgkmcnt(0)
	v_pk_add_f32 v[4:5], v[4:5], v[6:7]
	v_pk_add_f32 v[18:19], v[18:19], v[24:25]
	v_pk_add_f32 v[20:21], v[20:21], v[26:27]
	v_pk_add_f32 v[22:23], v[22:23], v[28:29]
	ds_bpermute_b32 v6, v10, v4
	ds_bpermute_b32 v7, v10, v5
	ds_bpermute_b32 v24, v10, v18
	ds_bpermute_b32 v25, v10, v19
	ds_bpermute_b32 v26, v10, v20
	ds_bpermute_b32 v27, v10, v21
	ds_bpermute_b32 v28, v10, v22
	ds_bpermute_b32 v29, v10, v23
	s_waitcnt lgkmcnt(0)
	v_pk_add_f32 v[4:5], v[4:5], v[6:7]
	v_pk_add_f32 v[18:19], v[18:19], v[24:25]
	v_pk_add_f32 v[20:21], v[20:21], v[26:27]
	v_pk_add_f32 v[22:23], v[22:23], v[28:29]
	ds_bpermute_b32 v6, v11, v4
	ds_bpermute_b32 v7, v11, v5
	ds_bpermute_b32 v24, v11, v18
	ds_bpermute_b32 v25, v11, v19
	ds_bpermute_b32 v26, v11, v20
	ds_bpermute_b32 v27, v11, v21
	ds_bpermute_b32 v28, v11, v22
	ds_bpermute_b32 v29, v11, v23
	s_waitcnt lgkmcnt(0)
	v_pk_add_f32 v[4:5], v[4:5], v[6:7]
	v_pk_add_f32 v[18:19], v[18:19], v[24:25]
	v_pk_add_f32 v[20:21], v[20:21], v[26:27]
	v_pk_add_f32 v[22:23], v[22:23], v[28:29]
	ds_bpermute_b32 v6, v12, v4
	ds_bpermute_b32 v7, v12, v5
	ds_bpermute_b32 v24, v12, v18
	ds_bpermute_b32 v25, v12, v19
	ds_bpermute_b32 v26, v12, v20
	ds_bpermute_b32 v27, v12, v21
	ds_bpermute_b32 v28, v12, v22
	ds_bpermute_b32 v29, v12, v23
	s_waitcnt lgkmcnt(0)
	v_pk_add_f32 v[4:5], v[4:5], v[6:7]
	v_pk_add_f32 v[18:19], v[18:19], v[24:25]
	v_pk_add_f32 v[20:21], v[20:21], v[26:27]
	v_pk_add_f32 v[22:23], v[22:23], v[28:29]
	ds_bpermute_b32 v6, v13, v4
	ds_bpermute_b32 v7, v13, v5
	ds_bpermute_b32 v24, v13, v18
	ds_bpermute_b32 v25, v13, v19
	ds_bpermute_b32 v26, v13, v20
	ds_bpermute_b32 v27, v13, v21
	ds_bpermute_b32 v28, v13, v22
	ds_bpermute_b32 v29, v13, v23
	s_waitcnt lgkmcnt(0)
	v_pk_add_f32 v[4:5], v[4:5], v[6:7]
	v_pk_add_f32 v[18:19], v[18:19], v[24:25]
	v_pk_add_f32 v[20:21], v[20:21], v[26:27]
	v_pk_add_f32 v[22:23], v[22:23], v[28:29]
	s_and_saveexec_b64 s[20:21], s[0:1]
	s_cbranch_execz .Lsr_done
	s_nop 0
	v_pk_mul_f32 v[4:5], v[4:5], s[18:19] op_sel_hi:[1,0]
	s_nop 0
	v_fma_f32 v5, -v4, v4, v5
	v_max_f32_e32 v5, 0, v5
	v_add_f32_e32 v5, 0x358637bd, v5
	v_mul_f32_e32 v6, 0x4f800000, v5
	v_cmp_gt_f32_e32 vcc, s3, v5
	s_nop 1
	v_cndmask_b32_e32 v5, v5, v6, vcc
	v_sqrt_f32_e32 v6, v5
	s_nop 0
	v_add_u32_e32 v7, -1, v6
	v_fma_f32 v15, -v7, v6, v5
	v_add_u32_e32 v14, 1, v6
	v_cmp_ge_f32_e64 s[6:7], 0, v15
	s_nop 1
	v_cndmask_b32_e64 v7, v6, v7, s[6:7]
	v_fma_f32 v6, -v14, v6, v5
	v_cmp_lt_f32_e64 s[6:7], 0, v6
	s_nop 1
	v_cndmask_b32_e64 v6, v7, v14, s[6:7]
	v_mul_f32_e32 v7, 0x37800000, v6
	v_cndmask_b32_e32 v6, v6, v7, vcc
	v_cmp_class_f32_e32 vcc, v5, v0
	s_nop 1
	v_cndmask_b32_e32 v5, v6, v5, vcc
	v_div_scale_f32 v6, s[6:7], v5, v5, 1.0
	v_rcp_f32_e32 v7, v6
	s_nop 0
	v_fma_f32 v14, -v6, v7, 1.0
	v_fmac_f32_e32 v7, v14, v7
	v_div_scale_f32 v14, vcc, 1.0, v5, 1.0
	v_mul_f32_e32 v15, v14, v7
	v_fma_f32 v16, -v6, v15, v14
	v_fmac_f32_e32 v15, v16, v7
	v_fma_f32 v6, -v6, v15, v14
	v_div_fmas_f32 v6, v6, v7, v15
	v_div_fixup_f32 v5, v6, v5, 1.0
	global_store_dwordx2 v1, v[4:5], s[8:9]
	s_add_u32 s8, s8, s14
	s_addc_u32 s9, s9, s15
	s_nop 0
	v_pk_mul_f32 v[18:19], v[18:19], s[18:19] op_sel_hi:[1,0]
	s_nop 0
	v_fma_f32 v19, -v18, v18, v19
	v_max_f32_e32 v19, 0, v19
	v_add_f32_e32 v19, 0x358637bd, v19
	v_mul_f32_e32 v6, 0x4f800000, v19
	v_cmp_gt_f32_e32 vcc, s3, v19
	s_nop 1
	v_cndmask_b32_e32 v19, v19, v6, vcc
	v_sqrt_f32_e32 v6, v19
	s_nop 0
	v_add_u32_e32 v7, -1, v6
	v_fma_f32 v15, -v7, v6, v19
	v_add_u32_e32 v14, 1, v6
	v_cmp_ge_f32_e64 s[6:7], 0, v15
	s_nop 1
	v_cndmask_b32_e64 v7, v6, v7, s[6:7]
	v_fma_f32 v6, -v14, v6, v19
	v_cmp_lt_f32_e64 s[6:7], 0, v6
	s_nop 1
	v_cndmask_b32_e64 v6, v7, v14, s[6:7]
	v_mul_f32_e32 v7, 0x37800000, v6
	v_cndmask_b32_e32 v6, v6, v7, vcc
	v_cmp_class_f32_e32 vcc, v19, v0
	s_nop 1
	v_cndmask_b32_e32 v19, v6, v19, vcc
	v_div_scale_f32 v6, s[6:7], v19, v19, 1.0
	v_rcp_f32_e32 v7, v6
	s_nop 0
	v_fma_f32 v14, -v6, v7, 1.0
	v_fmac_f32_e32 v7, v14, v7
	v_div_scale_f32 v14, vcc, 1.0, v19, 1.0
	v_mul_f32_e32 v15, v14, v7
	v_fma_f32 v16, -v6, v15, v14
	v_fmac_f32_e32 v15, v16, v7
	v_fma_f32 v6, -v6, v15, v14
	v_div_fmas_f32 v6, v6, v7, v15
	v_div_fixup_f32 v19, v6, v19, 1.0
	global_store_dwordx2 v1, v[18:19], s[8:9]
	s_add_u32 s8, s8, s14
	s_addc_u32 s9, s9, s15
	s_nop 0
	v_pk_mul_f32 v[20:21], v[20:21], s[18:19] op_sel_hi:[1,0]
	s_nop 0
	v_fma_f32 v21, -v20, v20, v21
	v_max_f32_e32 v21, 0, v21
	v_add_f32_e32 v21, 0x358637bd, v21
	v_mul_f32_e32 v6, 0x4f800000, v21
	v_cmp_gt_f32_e32 vcc, s3, v21
	s_nop 1
	v_cndmask_b32_e32 v21, v21, v6, vcc
	v_sqrt_f32_e32 v6, v21
	s_nop 0
	v_add_u32_e32 v7, -1, v6
	v_fma_f32 v15, -v7, v6, v21
	v_add_u32_e32 v14, 1, v6
	v_cmp_ge_f32_e64 s[6:7], 0, v15
	s_nop 1
	v_cndmask_b32_e64 v7, v6, v7, s[6:7]
	v_fma_f32 v6, -v14, v6, v21
	v_cmp_lt_f32_e64 s[6:7], 0, v6
	s_nop 1
	v_cndmask_b32_e64 v6, v7, v14, s[6:7]
	v_mul_f32_e32 v7, 0x37800000, v6
	v_cndmask_b32_e32 v6, v6, v7, vcc
	v_cmp_class_f32_e32 vcc, v21, v0
	s_nop 1
	v_cndmask_b32_e32 v21, v6, v21, vcc
	v_div_scale_f32 v6, s[6:7], v21, v21, 1.0
	v_rcp_f32_e32 v7, v6
	s_nop 0
	v_fma_f32 v14, -v6, v7, 1.0
	v_fmac_f32_e32 v7, v14, v7
	v_div_scale_f32 v14, vcc, 1.0, v21, 1.0
	v_mul_f32_e32 v15, v14, v7
	v_fma_f32 v16, -v6, v15, v14
	v_fmac_f32_e32 v15, v16, v7
	v_fma_f32 v6, -v6, v15, v14
	v_div_fmas_f32 v6, v6, v7, v15
	v_div_fixup_f32 v21, v6, v21, 1.0
	global_store_dwordx2 v1, v[20:21], s[8:9]
	s_add_u32 s8, s8, s14
	s_addc_u32 s9, s9, s15
	s_nop 0
	v_pk_mul_f32 v[22:23], v[22:23], s[18:19] op_sel_hi:[1,0]
	s_nop 0
	v_fma_f32 v23, -v22, v22, v23
	v_max_f32_e32 v23, 0, v23
	v_add_f32_e32 v23, 0x358637bd, v23
	v_mul_f32_e32 v6, 0x4f800000, v23
	v_cmp_gt_f32_e32 vcc, s3, v23
	s_nop 1
	v_cndmask_b32_e32 v23, v23, v6, vcc
	v_sqrt_f32_e32 v6, v23
	s_nop 0
	v_add_u32_e32 v7, -1, v6
	v_fma_f32 v15, -v7, v6, v23
	v_add_u32_e32 v14, 1, v6
	v_cmp_ge_f32_e64 s[6:7], 0, v15
	s_nop 1
	v_cndmask_b32_e64 v7, v6, v7, s[6:7]
	v_fma_f32 v6, -v14, v6, v23
	v_cmp_lt_f32_e64 s[6:7], 0, v6
	s_nop 1
	v_cndmask_b32_e64 v6, v7, v14, s[6:7]
	v_mul_f32_e32 v7, 0x37800000, v6
	v_cndmask_b32_e32 v6, v6, v7, vcc
	v_cmp_class_f32_e32 vcc, v23, v0
	s_nop 1
	v_cndmask_b32_e32 v23, v6, v23, vcc
	v_div_scale_f32 v6, s[6:7], v23, v23, 1.0
	v_rcp_f32_e32 v7, v6
	s_nop 0
	v_fma_f32 v14, -v6, v7, 1.0
	v_fmac_f32_e32 v7, v14, v7
	v_div_scale_f32 v14, vcc, 1.0, v23, 1.0
	v_mul_f32_e32 v15, v14, v7
	v_fma_f32 v16, -v6, v15, v14
	v_fmac_f32_e32 v15, v16, v7
	v_fma_f32 v6, -v6, v15, v14
	v_div_fmas_f32 v6, v6, v7, v15
	v_div_fixup_f32 v23, v6, v23, 1.0
	global_store_dwordx2 v1, v[22:23], s[8:9]
.Lsr_done:
	s_or_b64 exec, exec, s[20:21]
.LBB0_488:
	s_cmp_gt_u32 s77, 4
	s_cselect_b64 s[0:1], -1, 0
	s_and_b64 s[0:1], s[12:13], s[0:1]
	s_andn2_b64 vcc, exec, s[0:1]
	s_cbranch_vccnz .LBB0_542
	s_waitcnt vmcnt(0)
	s_waitcnt lgkmcnt(0)
	s_barrier
	s_and_saveexec_b64 s[0:1], s[84:85]
	s_cbranch_execz .LBB0_541
	s_add_i32 s3, 0, 0x21ff0
	v_mov_b32_e32 v0, s3
	s_waitcnt vmcnt(0) expcnt(0) lgkmcnt(0)
	ds_read_b32 v2, v0
	s_add_i32 s3, 0, 0x21ff4
	v_mov_b32_e32 v0, s3
	ds_read_b32 v0, v0
	s_waitcnt lgkmcnt(1)
	v_cmp_ne_u32_e32 vcc, 0, v2
	s_cbranch_vccnz .LBB0_505
	s_add_u32 s6, s70, 0x3ac94200
	s_addc_u32 s7, s71, 0
	s_add_u32 s8, s70, 0x3ac94400
	s_addc_u32 s9, s71, 0
	s_add_u32 s12, s70, 0x3ac94500
	s_addc_u32 s13, s71, 0
	s_add_u32 s14, s70, 0x3ac94600
	s_addc_u32 s15, s71, 0
	s_add_u32 s16, s70, 0x3ac94700
	s_addc_u32 s17, s71, 0
	s_add_u32 s18, s70, 0x3ac94800
	s_addc_u32 s19, s71, 0
	s_add_u32 s20, s70, 0x3ac94900
	s_addc_u32 s21, s71, 0
	s_add_u32 s22, s70, 0x3ac94a00
	s_addc_u32 s23, s71, 0
	s_add_u32 s24, s70, 0x3ac94b00
	s_addc_u32 s25, s71, 0
	s_add_u32 s26, s70, 0x3ac94c00
	s_addc_u32 s27, s71, 0
	s_add_u32 s28, s70, 0x3ac94d00
	s_addc_u32 s29, s71, 0
	s_add_u32 s30, s70, 0x3ac94e00
	s_addc_u32 s31, s71, 0
	s_add_u32 s34, s70, 0x3ac94f00
	s_addc_u32 s35, s71, 0
	s_add_u32 s36, s70, 0x3ac95000
	s_addc_u32 s37, s71, 0
	s_add_u32 s38, s70, 0x3ac95100
	s_addc_u32 s39, s71, 0
	s_add_u32 s44, s70, 0x3ac95200
	s_addc_u32 s45, s71, 0
	s_add_u32 s48, s70, 0x3ac95300
	s_addc_u32 s49, s71, 0
	s_mov_b32 s3, 1
	v_mov_b32_e32 v16, 0
	s_branch .LBB0_493
